# adds reversed KV-GEMM tile assignment so WGs with one Q tile take the third KV round (load balance)
# speedup vs baseline: 1.0217x; 1.0052x over previous
.LBB0_960:
	s_and_b64 s[4:5], s[94:95], exec
	s_cselect_b32 s4, 0x100000, 0
	s_add_u32 s4, s10, s4
	s_addc_u32 s5, s11, 0
	s_add_u32 s4, s4, 0x640000
	s_addc_u32 s5, s5, 0
	v_mov_b32_e32 v0, v187
	v_mov_b32_e32 v3, v186
	v_mov_b32_e32 v2, s5
	v_mov_b32_e32 v4, v186
	v_readfirstlane_b32 s5, v3
	v_readfirstlane_b32 s6, v0
	s_add_u32 s5, s5, 0xfd80000
	s_addc_u32 s6, s6, 0
	v_mov_b32_e32 v0, v187
	v_mov_b32_e32 v3, s6
	v_mov_b32_e32 v5, v186
	v_readfirstlane_b32 s6, v4
	v_readfirstlane_b32 s7, v0
	s_add_u32 s6, s6, 0x12180000
	s_addc_u32 s7, s7, 0
	v_mov_b32_e32 v0, v187
	v_mov_b32_e32 v4, s7
	v_readlane_b32 s54, v255, 20
	v_readfirstlane_b32 s7, v5
	v_readfirstlane_b32 s8, v0
	s_add_u32 s7, s7, 0xc240000
	s_addc_u32 s8, s8, 0
	v_mov_b32_e32 v5, s8
	v_mov_b32_e32 v0, v189
	v_mov_b32_e32 v6, s7
	v_readlane_b32 s55, v255, 21
	v_readfirstlane_b32 s9, v5
	v_mov_b32_e32 v5, s4
	v_readfirstlane_b32 s8, v6
	v_readfirstlane_b32 s10, v5
	v_readfirstlane_b32 s11, v2
	v_mov_b32_e32 v2, v1
	v_mov_b32_e32 v5, v1
	s_andn2_b64 vcc, exec, s[54:55]
	v_mov_b32_e32 v2, s5
	s_nop 0
	v_readfirstlane_b32 s4, v2
	v_mov_b32_e32 v2, s6
	v_readfirstlane_b32 s5, v3
	v_readfirstlane_b32 s6, v2
	v_mov_b32_e32 v2, v1
	v_mov_b32_e32 v3, v1
	v_readfirstlane_b32 s7, v4
	v_mov_b32_e32 v2, v1
	v_mov_b32_e32 v3, v1
	s_nop 0
	v_mov_b32_e32 v2, v1
	v_mov_b32_e32 v3, v1
	s_nop 0
	v_mov_b32_e32 v2, v1
	v_mov_b32_e32 v3, v1
	s_cbranch_vccnz .LBB0_996
	v_ashrrev_i32_e32 v2, 3, v0
	v_bfe_u32 v3, v0, 5, 1
	v_and_b32_e32 v4, 31, v0
	s_waitcnt vmcnt(21)
	v_and_b32_e32 v162, 0xc0, v0
	v_lshlrev_b32_e32 v5, 4, v0
	s_movk_i32 s20, 0x90
	v_ashrrev_i32_e32 v6, 1, v0
	s_movk_i32 s54, 0xff80
	v_and_b32_e32 v0, 0xdf, v0
	v_and_b32_e32 v5, 0x70, v5
	v_and_or_b32 v163, v6, s54, v4
	v_mul_u32_u24_e32 v4, 0x90, v0
	v_mad_u32_u24 v8, v0, s20, v212
	v_mov_b32_e32 v0, 0xffffff80
	v_lshl_or_b32 v164, v2, 9, v5
	v_mul_lo_u32 v2, v2, s20
	s_waitcnt vmcnt(16)
	v_mul_lo_u32 v184, v163, s20
	v_lshl_or_b32 v190, v3, 2, v0
	v_lshlrev_b32_e32 v0, 3, v3
	v_lshlrev_b32_e32 v185, 4, v3
	v_add_u32_e32 v6, 0x12000, v2
	v_add_u32_e32 v7, 0x12000, v184
	v_lshl_add_u64 v[166:167], s[4:5], 0, v[0:1]
	s_movk_i32 s4, 0x7f
	v_mov_b32_e32 v165, v1
	v_cmp_lt_u32_e32 vcc, s4, v162
	v_or_b32_e32 v191, 32, v162
	v_add_u32_e32 v192, v4, v185
	v_add_u32_e32 v193, v6, v5
	v_add_u32_e32 v194, v7, v185
	v_add_u32_e32 v195, v8, v185
	v_add_u32_e32 v196, v5, v2
	s_sub_i32 s59, s3, s73
	s_add_i32 s59, s59, -1
	s_branch .LBB0_963
